# double-tile GEMM (2 stacked 128x128 tiles share the weight tile, B double-buffered, SGPR-addressed DMA) in phases B and J; E/D/C loops mid-release
# speedup vs baseline: 1.0236x; 1.0124x over previous
.LBB0_21:
	s_mul_hi_u32 s30, s27, 0xcccccccd
	s_lshr_b32 s30, s30, 4
	s_mul_i32 s26, s30, 20
	s_sub_i32 s36, s27, s26
	s_lshl_b32 s36, s36, 1
	v_writelane_b32 v255, s36, 57
	v_writelane_b32 v255, s30, 58
	v_mov_b32_e32 v2, v208
	s_ashr_i32 s37, s36, 31
	v_ashrrev_i32_e32 v3, 6, v2
	v_lshrrev_b32_e32 v0, 3, v2
	v_bfe_u32 v1, v2, 3, 3
	v_lshlrev_b32_e32 v5, 5, v3
	s_lshl_b64 s[40:41], s[36:37], 18
	v_readlane_b32 s44, v251, 27
	v_bitop3_b32 v4, v0, v2, 7 bitop3:0x28
	v_or_b32_e32 v0, v5, v1
	v_readlane_b32 s45, v251, 28
	s_add_u32 s40, s44, s40
	v_ashrrev_i32_e32 v1, 31, v0
	s_addc_u32 s41, s45, s41
	v_lshlrev_b64 v[0:1], 11, v[0:1]
	v_lshl_add_u64 v[0:1], s[40:41], 0, v[0:1]
	v_lshlrev_b32_e32 v128, 4, v4
	v_lshl_add_u64 v[64:65], v[0:1], 0, v[128:129]
	v_lshrrev_b32_e32 v0, 2, v2
	s_ashr_i32 s31, s30, 31
	v_and_b32_e32 v0, 8, v0
	v_bfe_u32 v1, v2, 3, 2
	s_lshl_b64 s[44:45], s[30:31], 18
	v_or3_b32 v0, v0, v1, v5
	s_add_u32 s44, s24, s44
	v_ashrrev_i32_e32 v1, 31, v0
	s_addc_u32 s45, s25, s45
	v_lshlrev_b64 v[0:1], 11, v[0:1]
	v_lshl_add_u64 v[0:1], s[44:45], 0, v[0:1]
	v_lshlrev_b32_e32 v80, 12, v3
	v_lshl_add_u64 v[66:67], v[0:1], 0, v[128:129]
	v_readfirstlane_b32 s26, v80
	v_or_b32_e32 v0, 0x400, v80
	s_waitcnt lgkmcnt(0)
	s_barrier
	s_mov_b32 m0, s26
	s_mov_b64 s[40:41], 0x4000
	v_readfirstlane_b32 s26, v0
	v_or_b32_e32 v0, 0x800, v80
	global_load_lds_dwordx4 v[64:65], off
	v_lshl_add_u64 v[68:69], v[64:65], 0, s[40:41]
	s_mov_b32 m0, s26
	s_mov_b64 s[40:41], 0x8000
	v_readfirstlane_b32 s26, v0
	v_or_b32_e32 v0, 0xc00, v80
	global_load_lds_dwordx4 v[68:69], off
	v_lshl_add_u64 v[70:71], v[64:65], 0, s[40:41]
	s_mov_b32 m0, s26
	s_mov_b64 s[44:45], 0xc000
	v_readfirstlane_b32 s26, v0
	v_add_u32_e32 v0, 0x4000, v80
	global_load_lds_dwordx4 v[70:71], off
	v_lshl_add_u64 v[72:73], v[64:65], 0, s[44:45]
	s_mov_b32 m0, s26
	v_readfirstlane_b32 s26, v0
	v_add_u32_e32 v0, 0x4400, v80
	global_load_lds_dwordx4 v[72:73], off
	s_mov_b32 m0, s26
	v_readfirstlane_b32 s26, v0
	v_add_u32_e32 v0, 0x4800, v80
	global_load_lds_dwordx4 v[66:67], off
	v_lshl_add_u64 v[74:75], v[66:67], 0, s[40:41]
	s_mov_b32 m0, s26
	s_mov_b64 s[40:41], 0x2000
	v_readfirstlane_b32 s26, v0
	v_add_u32_e32 v0, 0x4c00, v80
	global_load_lds_dwordx4 v[74:75], off
	v_lshl_add_u64 v[76:77], v[66:67], 0, s[40:41]
	s_mov_b32 m0, s26
	s_mov_b64 s[40:41], 0xa000
	v_readfirstlane_b32 s26, v0
	global_load_lds_dwordx4 v[76:77], off
	v_lshl_add_u64 v[78:79], v[66:67], 0, s[40:41]
	s_mov_b32 m0, s26
	v_and_b32_e32 v0, 7, v2
	global_load_lds_dwordx4 v[78:79], off
	v_lshlrev_b32_e32 v1, 7, v2
	v_lshlrev_b32_e32 v0, 4, v0
	v_and_b32_e32 v1, 0x780, v1
	v_bitop3_b32 v0, v0, v2, 48 bitop3:0x78
	v_or_b32_e32 v81, v0, v1
	v_bitop3_b32 v82, v0, 64, v1 bitop3:0x36
	v_lshlrev_b32_e32 v0, 6, v2
	v_and_b32_e32 v83, 0xffffe000, v0
	v_lshlrev_b32_e32 v0, 13, v3
	v_and_b32_e32 v0, 0x2000, v0
	v_or_b32_e32 v84, 0x4000, v0
	v_mov_b32_e32 v0, 0
	s_mov_b32 s26, 64
	s_mov_b32 s31, 0
	v_mov_b32_e32 v1, v0
	v_mov_b32_e32 v2, v0
	v_mov_b32_e32 v3, v0
	v_mov_b32_e32 v4, v0
	v_mov_b32_e32 v5, v0
	v_mov_b32_e32 v6, v0
	v_mov_b32_e32 v7, v0
	v_mov_b32_e32 v8, v0
	v_mov_b32_e32 v9, v0
	v_mov_b32_e32 v10, v0
	v_mov_b32_e32 v11, v0
	v_mov_b32_e32 v12, v0
	v_mov_b32_e32 v13, v0
	v_mov_b32_e32 v14, v0
	v_mov_b32_e32 v15, v0
	v_mov_b32_e32 v16, v0
	v_mov_b32_e32 v17, v0
	v_mov_b32_e32 v18, v0
	v_mov_b32_e32 v19, v0
	v_mov_b32_e32 v20, v0
	v_mov_b32_e32 v21, v0
	v_mov_b32_e32 v22, v0
	v_mov_b32_e32 v23, v0
	v_mov_b32_e32 v24, v0
	v_mov_b32_e32 v25, v0
	v_mov_b32_e32 v26, v0
	v_mov_b32_e32 v27, v0
	v_mov_b32_e32 v28, v0
	v_mov_b32_e32 v29, v0
	v_mov_b32_e32 v30, v0
	v_mov_b32_e32 v31, v0
	v_mov_b32_e32 v32, v0
	v_mov_b32_e32 v33, v0
	v_mov_b32_e32 v34, v0
	v_mov_b32_e32 v35, v0
	v_mov_b32_e32 v36, v0
	v_mov_b32_e32 v37, v0
	v_mov_b32_e32 v38, v0
	v_mov_b32_e32 v39, v0
	v_mov_b32_e32 v40, v0
	v_mov_b32_e32 v41, v0
	v_mov_b32_e32 v42, v0
	v_mov_b32_e32 v43, v0
	v_mov_b32_e32 v44, v0
	v_mov_b32_e32 v45, v0
	v_mov_b32_e32 v46, v0
	v_mov_b32_e32 v47, v0
	v_mov_b32_e32 v48, v0
	v_mov_b32_e32 v49, v0
	v_mov_b32_e32 v50, v0
	v_mov_b32_e32 v51, v0
	v_mov_b32_e32 v52, v0
	v_mov_b32_e32 v53, v0
	v_mov_b32_e32 v54, v0
	v_mov_b32_e32 v55, v0
	v_mov_b32_e32 v56, v0
	v_mov_b32_e32 v57, v0
	v_mov_b32_e32 v58, v0
	v_mov_b32_e32 v59, v0
	v_mov_b32_e32 v60, v0
	v_mov_b32_e32 v61, v0
	v_mov_b32_e32 v62, v0
	v_mov_b32_e32 v63, v0
	v_readlane_b32 s40, v251, 27
	v_readlane_b32 s41, v251, 28
	v_readlane_b32 s36, v255, 57
	s_lshl_b32 s36, s36, 18
	s_add_u32 s40, s40, s36
	s_addc_u32 s41, s41, 0
	v_readlane_b32 s36, v255, 58
	s_lshl_b32 s36, s36, 18
	s_add_u32 s44, s24, s36
	s_addc_u32 s45, s25, 0
	v_add_u32_e32 v126, v83, v81
	v_add_u32_e32 v133, v83, v82
	v_add_u32_e32 v127, v84, v81
	v_add_u32_e32 v128, v84, v82
	v_readfirstlane_b32 s28, v80
	v_subrev_u32_e32 v82, s40, v64
	v_subrev_u32_e32 v83, s44, v66
	s_add_u32 m0, s28, 0x8000
	s_add_u32 s30, s40, 0x40000
	s_addc_u32 s31, s41, 0
	global_load_lds_dwordx4 v82, s[30:31]
	s_add_u32 m0, s28, 0x8400
	s_add_u32 s30, s40, 0x44000
	s_addc_u32 s31, s41, 0
	global_load_lds_dwordx4 v82, s[30:31]
	s_add_u32 m0, s28, 0x8800
	s_add_u32 s30, s40, 0x48000
	s_addc_u32 s31, s41, 0
	global_load_lds_dwordx4 v82, s[30:31]
	s_add_u32 m0, s28, 0x8c00
	s_add_u32 s30, s40, 0x4c000
	s_addc_u32 s31, s41, 0
	global_load_lds_dwordx4 v82, s[30:31]
	v_mov_b32_e32 v160, 0
	v_mov_b32_e32 v161, 0
	v_mov_b32_e32 v162, 0
	v_mov_b32_e32 v163, 0
	v_mov_b32_e32 v164, 0
	v_mov_b32_e32 v165, 0
	v_mov_b32_e32 v166, 0
	v_mov_b32_e32 v167, 0
	v_mov_b32_e32 v168, 0
	v_mov_b32_e32 v169, 0
	v_mov_b32_e32 v170, 0
	v_mov_b32_e32 v171, 0
	v_mov_b32_e32 v172, 0
	v_mov_b32_e32 v173, 0
	v_mov_b32_e32 v174, 0
	v_mov_b32_e32 v175, 0
	v_mov_b32_e32 v176, 0
	v_mov_b32_e32 v177, 0
	v_mov_b32_e32 v178, 0
	v_mov_b32_e32 v179, 0
	v_mov_b32_e32 v180, 0
	v_mov_b32_e32 v181, 0
	v_mov_b32_e32 v182, 0
	v_mov_b32_e32 v183, 0
	v_mov_b32_e32 v184, 0
	v_mov_b32_e32 v185, 0
	v_mov_b32_e32 v186, 0
	v_mov_b32_e32 v187, 0
	v_mov_b32_e32 v188, 0
	v_mov_b32_e32 v189, 0
	v_mov_b32_e32 v190, 0
	v_mov_b32_e32 v191, 0
	v_mov_b32_e32 v192, 0
	v_mov_b32_e32 v193, 0
	v_mov_b32_e32 v194, 0
	v_mov_b32_e32 v195, 0
	v_mov_b32_e32 v196, 0
	v_mov_b32_e32 v197, 0
	v_mov_b32_e32 v198, 0
	v_mov_b32_e32 v199, 0
	v_mov_b32_e32 v200, 0
	v_mov_b32_e32 v201, 0
	v_mov_b32_e32 v202, 0
	v_mov_b32_e32 v203, 0
	v_mov_b32_e32 v204, 0
	v_mov_b32_e32 v205, 0
	v_mov_b32_e32 v206, 0
	v_mov_b32_e32 v207, 0
	v_mov_b32_e32 v232, 0
	v_mov_b32_e32 v233, 0
	v_mov_b32_e32 v234, 0
	v_mov_b32_e32 v235, 0
	v_mov_b32_e32 v236, 0
	v_mov_b32_e32 v237, 0
	v_mov_b32_e32 v238, 0
	v_mov_b32_e32 v239, 0
	v_mov_b32_e32 v240, 0
	v_mov_b32_e32 v241, 0
	v_mov_b32_e32 v242, 0
	v_mov_b32_e32 v243, 0
	v_mov_b32_e32 v244, 0
	v_mov_b32_e32 v245, 0
	v_mov_b32_e32 v246, 0
	v_mov_b32_e32 v247, 0
	s_mov_b32 s26, 0
	s_mov_b32 s37, 0
.LBB0_22:
	s_waitcnt vmcnt(0)
	s_waitcnt lgkmcnt(0)
	s_barrier
	s_add_i32 s36, s26, 64
	s_cmp_ge_i32 s36, 1024
	s_cbranch_scc1 .LdtJ_nb
	s_xor_b32 s36, s37, 0x8000
	s_add_u32 s36, s36, s28
	s_add_u32 m0, s36, 0x4000
	s_add_u32 s30, s44, 0x80
	s_addc_u32 s31, s45, 0
	global_load_lds_dwordx4 v83, s[30:31]
	s_add_u32 m0, s36, 0x4400
	s_add_u32 s30, s44, 0x8080
	s_addc_u32 s31, s45, 0
	global_load_lds_dwordx4 v83, s[30:31]
	s_add_u32 m0, s36, 0x4800
	s_add_u32 s30, s44, 0x2080
	s_addc_u32 s31, s45, 0
	global_load_lds_dwordx4 v83, s[30:31]
	s_add_u32 m0, s36, 0x4c00
	s_add_u32 s30, s44, 0xa080
	s_addc_u32 s31, s45, 0
	global_load_lds_dwordx4 v83, s[30:31]
.LdtJ_nb:
	v_add_u32_e32 v80, s37, v127
	v_add_u32_e32 v81, s37, v128
	ds_read_b128 v[86:89], v126
	ds_read_b128 v[90:93], v126 offset:2048
	ds_read_b128 v[94:97], v126 offset:4096
	ds_read_b128 v[98:101], v126 offset:6144
	ds_read_b128 v[102:105], v80
	ds_read_b128 v[106:109], v80 offset:2048
	ds_read_b128 v[110:113], v80 offset:4096
	ds_read_b128 v[114:117], v80 offset:6144
	ds_read_b128 v[118:121], v133
	ds_read_b128 v[122:125], v133 offset:2048
	ds_read_b128 v[134:137], v133 offset:4096
	ds_read_b128 v[138:141], v133 offset:6144
	ds_read_b128 v[64:67], v126 offset:32768
	ds_read_b128 v[68:71], v126 offset:34816
	ds_read_b128 v[72:75], v126 offset:36864
	ds_read_b128 v[76:79], v126 offset:38912
	ds_read_b128 v[142:145], v81
	ds_read_b128 v[146:149], v81 offset:2048
	ds_read_b128 v[150:153], v81 offset:4096
	ds_read_b128 v[154:157], v81 offset:6144
	s_waitcnt lgkmcnt(12)
	v_mfma_f32_16x16x32_bf16 v[60:63], v[102:105], v[86:89], v[60:63]
	v_mfma_f32_16x16x32_bf16 v[56:59], v[106:109], v[86:89], v[56:59]
	v_mfma_f32_16x16x32_bf16 v[52:55], v[110:113], v[86:89], v[52:55]
	v_mfma_f32_16x16x32_bf16 v[48:51], v[114:117], v[86:89], v[48:51]
	v_mfma_f32_16x16x32_bf16 v[44:47], v[102:105], v[90:93], v[44:47]
	v_mfma_f32_16x16x32_bf16 v[40:43], v[106:109], v[90:93], v[40:43]
	v_mfma_f32_16x16x32_bf16 v[36:39], v[110:113], v[90:93], v[36:39]
	v_mfma_f32_16x16x32_bf16 v[32:35], v[114:117], v[90:93], v[32:35]
	v_mfma_f32_16x16x32_bf16 v[28:31], v[102:105], v[94:97], v[28:31]
	v_mfma_f32_16x16x32_bf16 v[24:27], v[106:109], v[94:97], v[24:27]
	v_mfma_f32_16x16x32_bf16 v[20:23], v[110:113], v[94:97], v[20:23]
	v_mfma_f32_16x16x32_bf16 v[12:15], v[102:105], v[98:101], v[12:15]
	v_mfma_f32_16x16x32_bf16 v[8:11], v[106:109], v[98:101], v[8:11]
	v_mfma_f32_16x16x32_bf16 v[4:7], v[110:113], v[98:101], v[4:7]
	v_mfma_f32_16x16x32_bf16 v[0:3], v[114:117], v[98:101], v[0:3]
	v_mfma_f32_16x16x32_bf16 v[16:19], v[114:117], v[94:97], v[16:19]
	ds_read_b128 v[86:89], v133 offset:32768
	ds_read_b128 v[90:93], v133 offset:34816
	ds_read_b128 v[94:97], v133 offset:36864
	ds_read_b128 v[98:101], v133 offset:38912
	s_waitcnt lgkmcnt(8)
	v_mfma_f32_16x16x32_bf16 v[244:247], v[102:105], v[64:67], v[244:247]
	v_mfma_f32_16x16x32_bf16 v[240:243], v[106:109], v[64:67], v[240:243]
	v_mfma_f32_16x16x32_bf16 v[236:239], v[110:113], v[64:67], v[236:239]
	v_mfma_f32_16x16x32_bf16 v[232:235], v[114:117], v[64:67], v[232:235]
	v_mfma_f32_16x16x32_bf16 v[204:207], v[102:105], v[68:71], v[204:207]
	v_mfma_f32_16x16x32_bf16 v[200:203], v[106:109], v[68:71], v[200:203]
	v_mfma_f32_16x16x32_bf16 v[196:199], v[110:113], v[68:71], v[196:199]
	v_mfma_f32_16x16x32_bf16 v[192:195], v[114:117], v[68:71], v[192:195]
	v_mfma_f32_16x16x32_bf16 v[188:191], v[102:105], v[72:75], v[188:191]
	v_mfma_f32_16x16x32_bf16 v[184:187], v[106:109], v[72:75], v[184:187]
	v_mfma_f32_16x16x32_bf16 v[180:183], v[110:113], v[72:75], v[180:183]
	v_mfma_f32_16x16x32_bf16 v[172:175], v[102:105], v[76:79], v[172:175]
	v_mfma_f32_16x16x32_bf16 v[168:171], v[106:109], v[76:79], v[168:171]
	v_mfma_f32_16x16x32_bf16 v[164:167], v[110:113], v[76:79], v[164:167]
	v_mfma_f32_16x16x32_bf16 v[160:163], v[114:117], v[76:79], v[160:163]
	v_mfma_f32_16x16x32_bf16 v[176:179], v[114:117], v[72:75], v[176:179]
	s_waitcnt lgkmcnt(0)
	s_barrier
	s_add_i32 s36, s26, 64
	s_cmp_ge_i32 s36, 1024
	s_cbranch_scc1 .LdtJ_na
	s_add_u32 m0, s28, 0x0
	s_add_u32 s30, s40, 0x80
	s_addc_u32 s31, s41, 0
	global_load_lds_dwordx4 v82, s[30:31]
	s_add_u32 m0, s28, 0x400
	s_add_u32 s30, s40, 0x4080
	s_addc_u32 s31, s41, 0
	global_load_lds_dwordx4 v82, s[30:31]
	s_add_u32 m0, s28, 0x800
	s_add_u32 s30, s40, 0x8080
	s_addc_u32 s31, s41, 0
	global_load_lds_dwordx4 v82, s[30:31]
	s_add_u32 m0, s28, 0xc00
	s_add_u32 s30, s40, 0xc080
	s_addc_u32 s31, s41, 0
	global_load_lds_dwordx4 v82, s[30:31]
	s_add_u32 m0, s28, 0x8000
	s_add_u32 s30, s40, 0x40080
	s_addc_u32 s31, s41, 0
	global_load_lds_dwordx4 v82, s[30:31]
	s_add_u32 m0, s28, 0x8400
	s_add_u32 s30, s40, 0x44080
	s_addc_u32 s31, s41, 0
	global_load_lds_dwordx4 v82, s[30:31]
	s_add_u32 m0, s28, 0x8800
	s_add_u32 s30, s40, 0x48080
	s_addc_u32 s31, s41, 0
	global_load_lds_dwordx4 v82, s[30:31]
	s_add_u32 m0, s28, 0x8c00
	s_add_u32 s30, s40, 0x4c080
	s_addc_u32 s31, s41, 0
	global_load_lds_dwordx4 v82, s[30:31]
.LdtJ_na:
	s_nop 0
	v_mfma_f32_16x16x32_bf16 v[60:63], v[142:145], v[118:121], v[60:63]
	v_mfma_f32_16x16x32_bf16 v[56:59], v[146:149], v[118:121], v[56:59]
	v_mfma_f32_16x16x32_bf16 v[52:55], v[150:153], v[118:121], v[52:55]
	v_mfma_f32_16x16x32_bf16 v[48:51], v[154:157], v[118:121], v[48:51]
	v_mfma_f32_16x16x32_bf16 v[44:47], v[142:145], v[122:125], v[44:47]
	v_mfma_f32_16x16x32_bf16 v[40:43], v[146:149], v[122:125], v[40:43]
	v_mfma_f32_16x16x32_bf16 v[36:39], v[150:153], v[122:125], v[36:39]
	v_mfma_f32_16x16x32_bf16 v[32:35], v[154:157], v[122:125], v[32:35]
	v_mfma_f32_16x16x32_bf16 v[28:31], v[142:145], v[134:137], v[28:31]
	v_mfma_f32_16x16x32_bf16 v[24:27], v[146:149], v[134:137], v[24:27]
	v_mfma_f32_16x16x32_bf16 v[20:23], v[150:153], v[134:137], v[20:23]
	v_mfma_f32_16x16x32_bf16 v[16:19], v[154:157], v[134:137], v[16:19]
	v_mfma_f32_16x16x32_bf16 v[12:15], v[142:145], v[138:141], v[12:15]
	v_mfma_f32_16x16x32_bf16 v[8:11], v[146:149], v[138:141], v[8:11]
	v_mfma_f32_16x16x32_bf16 v[4:7], v[150:153], v[138:141], v[4:7]
	v_mfma_f32_16x16x32_bf16 v[0:3], v[154:157], v[138:141], v[0:3]
	v_mfma_f32_16x16x32_bf16 v[244:247], v[142:145], v[86:89], v[244:247]
	v_mfma_f32_16x16x32_bf16 v[240:243], v[146:149], v[86:89], v[240:243]
	v_mfma_f32_16x16x32_bf16 v[236:239], v[150:153], v[86:89], v[236:239]
	v_mfma_f32_16x16x32_bf16 v[232:235], v[154:157], v[86:89], v[232:235]
	v_mfma_f32_16x16x32_bf16 v[204:207], v[142:145], v[90:93], v[204:207]
	v_mfma_f32_16x16x32_bf16 v[200:203], v[146:149], v[90:93], v[200:203]
	v_mfma_f32_16x16x32_bf16 v[196:199], v[150:153], v[90:93], v[196:199]
	v_mfma_f32_16x16x32_bf16 v[192:195], v[154:157], v[90:93], v[192:195]
	v_mfma_f32_16x16x32_bf16 v[188:191], v[142:145], v[94:97], v[188:191]
	v_mfma_f32_16x16x32_bf16 v[184:187], v[146:149], v[94:97], v[184:187]
	v_mfma_f32_16x16x32_bf16 v[180:183], v[150:153], v[94:97], v[180:183]
	v_mfma_f32_16x16x32_bf16 v[176:179], v[154:157], v[94:97], v[176:179]
	v_mfma_f32_16x16x32_bf16 v[172:175], v[142:145], v[98:101], v[172:175]
	v_mfma_f32_16x16x32_bf16 v[168:171], v[146:149], v[98:101], v[168:171]
	v_mfma_f32_16x16x32_bf16 v[164:167], v[150:153], v[98:101], v[164:167]
	v_mfma_f32_16x16x32_bf16 v[160:163], v[154:157], v[98:101], v[160:163]
	s_add_u32 s40, s40, 0x80
	s_addc_u32 s41, s41, 0
	s_add_u32 s44, s44, 0x80
	s_addc_u32 s45, s45, 0
	s_xor_b32 s37, s37, 0x8000
	s_add_i32 s26, s26, 64
	s_cmp_lt_i32 s26, 1024
	s_cbranch_scc1 .LBB0_22
	s_waitcnt vmcnt(0)
	v_mov_b32_e32 v64, v208
	s_waitcnt lgkmcnt(0)
	s_barrier
	s_mov_b32 s37, 0
	v_writelane_b32 v255, s37, 59
	v_readlane_b32 s36, v255, 57
	v_readlane_b32 s30, v255, 58
.LdtJ_epi:
	v_mov_b32_e32 v65, v208
	v_and_b32_e32 v67, 15, v64
	v_lshrrev_b32_e32 v64, 1, v64
	v_and_b32_e32 v64, 24, v64
	v_max_f32_e32 v60, v60, v60
	v_max_f32_e32 v61, v61, v61
	v_max_f32_e32 v62, v62, v62
	v_max_f32_e32 v63, v63, v63
	v_max_f32_e32 v56, v56, v56
	v_max_f32_e32 v57, v57, v57
	v_max_f32_e32 v58, v58, v58
	v_max_f32_e32 v60, 0, v60
	v_and_or_b32 v68, v65, 64, v64
	v_max_f32_e32 v61, 0, v61
	v_max_f32_e32 v62, 0, v62
	v_max_f32_e32 v63, 0, v63
	v_max_f32_e32 v56, 0, v56
	v_max_f32_e32 v57, 0, v57
	v_max_f32_e32 v64, 0, v58
	v_max_f32_e32 v58, v59, v59
	v_ashrrev_i32_e32 v66, 1, v65
	s_movk_i32 s26, 0xffc0
	v_max_f32_e32 v65, 0, v58
	v_pk_mul_f32 v[58:59], v[60:61], v[60:61]
	v_pk_mul_f32 v[60:61], v[62:63], v[62:63]
	v_pk_mul_f32 v[56:57], v[56:57], v[56:57]
	v_and_or_b32 v66, v66, s26, v67
	v_cvt_pk_bf16_f32 v58, v58, v59
	v_cvt_pk_bf16_f32 v59, v60, v61
	v_cvt_pk_bf16_f32 v60, v56, v57
	v_pk_mul_f32 v[56:57], v[64:65], v[64:65]
	s_lshl_b32 s30, s30, 7
	v_cvt_pk_bf16_f32 v61, v56, v57
	v_lshl_add_u32 v56, s36, 7, v66
	v_ashrrev_i32_e32 v57, 31, v56
	v_lshlrev_b64 v[62:63], 13, v[56:57]
	s_ashr_i32 s31, s30, 31
	v_lshl_add_u64 v[62:63], s[70:71], 0, v[62:63]
	s_lshl_b64 s[30:31], s[30:31], 1
	v_lshl_add_u64 v[62:63], v[62:63], 0, s[30:31]
	v_lshlrev_b32_e32 v128, 1, v68
	v_lshl_add_u64 v[62:63], v[62:63], 0, v[128:129]
	v_max_f32_e32 v48, v48, v48
	global_store_dwordx4 v[62:63], v[58:61], off
	v_max_f32_e32 v52, v52, v52
	v_max_f32_e32 v53, v53, v53
	v_max_f32_e32 v58, 0, v48
	v_max_f32_e32 v48, v49, v49
	v_max_f32_e32 v54, v54, v54
	v_max_f32_e32 v55, v55, v55
	v_max_f32_e32 v59, 0, v48
	v_max_f32_e32 v48, v50, v50
	v_max_f32_e32 v52, 0, v52
	v_max_f32_e32 v53, 0, v53
	v_max_f32_e32 v54, 0, v54
	v_max_f32_e32 v55, 0, v55
	v_max_f32_e32 v60, 0, v48
	v_max_f32_e32 v48, v51, v51
	v_max_f32_e32 v61, 0, v48
	v_pk_mul_f32 v[48:49], v[52:53], v[52:53]
	v_pk_mul_f32 v[50:51], v[54:55], v[54:55]
	v_cvt_pk_bf16_f32 v48, v48, v49
	v_cvt_pk_bf16_f32 v49, v50, v51
	v_pk_mul_f32 v[50:51], v[58:59], v[58:59]
	v_pk_mul_f32 v[52:53], v[60:61], v[60:61]
	v_cvt_pk_bf16_f32 v50, v50, v51
	v_cvt_pk_bf16_f32 v51, v52, v53
	v_max_f32_e32 v40, v40, v40
	global_store_dwordx4 v[62:63], v[48:51], off offset:64
	v_max_f32_e32 v44, v44, v44
	v_max_f32_e32 v45, v45, v45
	v_max_f32_e32 v48, 0, v40
	v_max_f32_e32 v40, v41, v41
	v_max_f32_e32 v46, v46, v46
	v_max_f32_e32 v47, v47, v47
	v_max_f32_e32 v49, 0, v40
	v_max_f32_e32 v40, v42, v42
	v_max_f32_e32 v44, 0, v44
	v_max_f32_e32 v45, 0, v45
	v_max_f32_e32 v46, 0, v46
	v_max_f32_e32 v47, 0, v47
	v_max_f32_e32 v50, 0, v40
	v_max_f32_e32 v40, v43, v43
	v_max_f32_e32 v51, 0, v40
	v_pk_mul_f32 v[40:41], v[44:45], v[44:45]
	v_pk_mul_f32 v[42:43], v[46:47], v[46:47]
	v_cvt_pk_bf16_f32 v40, v40, v41
	v_cvt_pk_bf16_f32 v41, v42, v43
	v_pk_mul_f32 v[42:43], v[48:49], v[48:49]
	v_pk_mul_f32 v[44:45], v[50:51], v[50:51]
	v_cvt_pk_bf16_f32 v42, v42, v43
	v_cvt_pk_bf16_f32 v43, v44, v45
	v_or_b32_e32 v44, 16, v56
	v_ashrrev_i32_e32 v45, 31, v44
	v_lshlrev_b64 v[44:45], 13, v[44:45]
	v_lshl_add_u64 v[44:45], s[70:71], 0, v[44:45]
	v_lshl_add_u64 v[44:45], v[44:45], 0, s[30:31]
	v_lshl_add_u64 v[44:45], v[44:45], 0, v[128:129]
	v_max_f32_e32 v32, v32, v32
	global_store_dwordx4 v[44:45], v[40:43], off
	v_max_f32_e32 v36, v36, v36
	v_max_f32_e32 v37, v37, v37
	v_max_f32_e32 v40, 0, v32
	v_max_f32_e32 v32, v33, v33
	v_max_f32_e32 v38, v38, v38
	v_max_f32_e32 v39, v39, v39
	v_max_f32_e32 v41, 0, v32
	v_max_f32_e32 v32, v34, v34
	v_max_f32_e32 v36, 0, v36
	v_max_f32_e32 v37, 0, v37
	v_max_f32_e32 v38, 0, v38
	v_max_f32_e32 v39, 0, v39
	v_max_f32_e32 v42, 0, v32
	v_max_f32_e32 v32, v35, v35
	v_max_f32_e32 v43, 0, v32
	v_pk_mul_f32 v[32:33], v[36:37], v[36:37]
	v_pk_mul_f32 v[34:35], v[38:39], v[38:39]
	v_cvt_pk_bf16_f32 v32, v32, v33
	v_cvt_pk_bf16_f32 v33, v34, v35
	v_pk_mul_f32 v[34:35], v[40:41], v[40:41]
	v_pk_mul_f32 v[36:37], v[42:43], v[42:43]
	v_cvt_pk_bf16_f32 v34, v34, v35
	v_cvt_pk_bf16_f32 v35, v36, v37
	v_max_f32_e32 v24, v24, v24
	global_store_dwordx4 v[44:45], v[32:35], off offset:64
	v_max_f32_e32 v28, v28, v28
	v_max_f32_e32 v29, v29, v29
	v_max_f32_e32 v32, 0, v24
	v_max_f32_e32 v24, v25, v25
	v_max_f32_e32 v30, v30, v30
	v_max_f32_e32 v31, v31, v31
	v_max_f32_e32 v33, 0, v24
	v_max_f32_e32 v24, v26, v26
	v_max_f32_e32 v28, 0, v28
	v_max_f32_e32 v29, 0, v29
	v_max_f32_e32 v30, 0, v30
	v_max_f32_e32 v31, 0, v31
	v_max_f32_e32 v34, 0, v24
	v_max_f32_e32 v24, v27, v27
	v_max_f32_e32 v35, 0, v24
	v_pk_mul_f32 v[24:25], v[28:29], v[28:29]
	v_pk_mul_f32 v[26:27], v[30:31], v[30:31]
	v_cvt_pk_bf16_f32 v24, v24, v25
	v_cvt_pk_bf16_f32 v25, v26, v27
	v_pk_mul_f32 v[26:27], v[32:33], v[32:33]
	v_pk_mul_f32 v[28:29], v[34:35], v[34:35]
	v_cvt_pk_bf16_f32 v26, v26, v27
	v_cvt_pk_bf16_f32 v27, v28, v29
	v_or_b32_e32 v28, 32, v56
	v_ashrrev_i32_e32 v29, 31, v28
	v_lshlrev_b64 v[28:29], 13, v[28:29]
	v_lshl_add_u64 v[28:29], s[70:71], 0, v[28:29]
	v_lshl_add_u64 v[28:29], v[28:29], 0, s[30:31]
	v_lshl_add_u64 v[28:29], v[28:29], 0, v[128:129]
	v_max_f32_e32 v16, v16, v16
	global_store_dwordx4 v[28:29], v[24:27], off
	v_max_f32_e32 v20, v20, v20
	v_max_f32_e32 v21, v21, v21
	v_max_f32_e32 v24, 0, v16
	v_max_f32_e32 v16, v17, v17
	v_max_f32_e32 v22, v22, v22
	v_max_f32_e32 v23, v23, v23
	v_max_f32_e32 v25, 0, v16
	v_max_f32_e32 v16, v18, v18
	v_max_f32_e32 v20, 0, v20
	v_max_f32_e32 v21, 0, v21
	v_max_f32_e32 v22, 0, v22
	v_max_f32_e32 v23, 0, v23
	v_max_f32_e32 v26, 0, v16
	v_max_f32_e32 v16, v19, v19
	v_max_f32_e32 v27, 0, v16
	v_pk_mul_f32 v[16:17], v[20:21], v[20:21]
	v_pk_mul_f32 v[18:19], v[22:23], v[22:23]
	v_cvt_pk_bf16_f32 v16, v16, v17
	v_cvt_pk_bf16_f32 v17, v18, v19
	v_pk_mul_f32 v[18:19], v[24:25], v[24:25]
	v_pk_mul_f32 v[20:21], v[26:27], v[26:27]
	v_cvt_pk_bf16_f32 v18, v18, v19
	v_cvt_pk_bf16_f32 v19, v20, v21
	v_max_f32_e32 v8, v8, v8
	global_store_dwordx4 v[28:29], v[16:19], off offset:64
	v_max_f32_e32 v12, v12, v12
	v_max_f32_e32 v13, v13, v13
	v_max_f32_e32 v16, 0, v8
	v_max_f32_e32 v8, v9, v9
	v_max_f32_e32 v14, v14, v14
	v_max_f32_e32 v15, v15, v15
	v_max_f32_e32 v17, 0, v8
	v_max_f32_e32 v8, v10, v10
	v_max_f32_e32 v12, 0, v12
	v_max_f32_e32 v13, 0, v13
	v_max_f32_e32 v14, 0, v14
	v_max_f32_e32 v15, 0, v15
	v_max_f32_e32 v18, 0, v8
	v_max_f32_e32 v8, v11, v11
	v_max_f32_e32 v19, 0, v8
	v_pk_mul_f32 v[8:9], v[12:13], v[12:13]
	v_pk_mul_f32 v[10:11], v[14:15], v[14:15]
	v_cvt_pk_bf16_f32 v8, v8, v9
	v_cvt_pk_bf16_f32 v9, v10, v11
	v_pk_mul_f32 v[10:11], v[16:17], v[16:17]
	v_pk_mul_f32 v[12:13], v[18:19], v[18:19]
	v_cvt_pk_bf16_f32 v10, v10, v11
	v_cvt_pk_bf16_f32 v11, v12, v13
	v_or_b32_e32 v12, 48, v56
	v_ashrrev_i32_e32 v13, 31, v12
	v_lshlrev_b64 v[12:13], 13, v[12:13]
	v_lshl_add_u64 v[12:13], s[70:71], 0, v[12:13]
	v_lshl_add_u64 v[12:13], v[12:13], 0, s[30:31]
	v_lshl_add_u64 v[12:13], v[12:13], 0, v[128:129]
	v_max_f32_e32 v0, v0, v0
	global_store_dwordx4 v[12:13], v[8:11], off
	v_max_f32_e32 v4, v4, v4
	v_max_f32_e32 v5, v5, v5
	v_max_f32_e32 v8, 0, v0
	v_max_f32_e32 v0, v1, v1
	v_max_f32_e32 v6, v6, v6
	v_max_f32_e32 v7, v7, v7
	v_max_f32_e32 v9, 0, v0
	v_max_f32_e32 v0, v2, v2
	v_max_f32_e32 v4, 0, v4
	v_max_f32_e32 v5, 0, v5
	v_max_f32_e32 v6, 0, v6
	v_max_f32_e32 v7, 0, v7
	v_max_f32_e32 v10, 0, v0
	v_max_f32_e32 v0, v3, v3
	v_max_f32_e32 v11, 0, v0
	v_pk_mul_f32 v[0:1], v[4:5], v[4:5]
	v_pk_mul_f32 v[2:3], v[6:7], v[6:7]
	v_cvt_pk_bf16_f32 v0, v0, v1
	v_cvt_pk_bf16_f32 v1, v2, v3
	v_pk_mul_f32 v[2:3], v[8:9], v[8:9]
	v_pk_mul_f32 v[4:5], v[10:11], v[10:11]
	v_cvt_pk_bf16_f32 v2, v2, v3
	v_cvt_pk_bf16_f32 v3, v4, v5
	global_store_dwordx4 v[12:13], v[0:3], off offset:64
	v_readlane_b32 s37, v255, 59
	s_cmp_lg_u32 s37, 0
	s_cbranch_scc1 .LdtJ_next
	s_mov_b32 s37, 1
	v_writelane_b32 v255, s37, 59
	v_readlane_b32 s36, v255, 57
	v_readlane_b32 s30, v255, 58
	s_add_i32 s36, s36, 1
	v_mov_b32_e32 v64, v208
	v_mov_b32_e32 v0, v160
	v_mov_b32_e32 v1, v161
	v_mov_b32_e32 v2, v162
	v_mov_b32_e32 v3, v163
	v_mov_b32_e32 v4, v164
	v_mov_b32_e32 v5, v165
	v_mov_b32_e32 v6, v166
	v_mov_b32_e32 v7, v167
	v_mov_b32_e32 v8, v168
	v_mov_b32_e32 v9, v169
	v_mov_b32_e32 v10, v170
	v_mov_b32_e32 v11, v171
	v_mov_b32_e32 v12, v172
	v_mov_b32_e32 v13, v173
	v_mov_b32_e32 v14, v174
	v_mov_b32_e32 v15, v175
	v_mov_b32_e32 v16, v176
	v_mov_b32_e32 v17, v177
	v_mov_b32_e32 v18, v178
	v_mov_b32_e32 v19, v179
	v_mov_b32_e32 v20, v180
	v_mov_b32_e32 v21, v181
	v_mov_b32_e32 v22, v182
	v_mov_b32_e32 v23, v183
	v_mov_b32_e32 v24, v184
	v_mov_b32_e32 v25, v185
	v_mov_b32_e32 v26, v186
	v_mov_b32_e32 v27, v187
	v_mov_b32_e32 v28, v188
	v_mov_b32_e32 v29, v189
	v_mov_b32_e32 v30, v190
	v_mov_b32_e32 v31, v191
	v_mov_b32_e32 v32, v192
	v_mov_b32_e32 v33, v193
	v_mov_b32_e32 v34, v194
	v_mov_b32_e32 v35, v195
	v_mov_b32_e32 v36, v196
	v_mov_b32_e32 v37, v197
	v_mov_b32_e32 v38, v198
	v_mov_b32_e32 v39, v199
	v_mov_b32_e32 v40, v200
	v_mov_b32_e32 v41, v201
	v_mov_b32_e32 v42, v202
	v_mov_b32_e32 v43, v203
	v_mov_b32_e32 v44, v204
	v_mov_b32_e32 v45, v205
	v_mov_b32_e32 v46, v206
	v_mov_b32_e32 v47, v207
	v_mov_b32_e32 v48, v232
	v_mov_b32_e32 v49, v233
	v_mov_b32_e32 v50, v234
	v_mov_b32_e32 v51, v235
	v_mov_b32_e32 v52, v236
	v_mov_b32_e32 v53, v237
	v_mov_b32_e32 v54, v238
	v_mov_b32_e32 v55, v239
	v_mov_b32_e32 v56, v240
	v_mov_b32_e32 v57, v241
	v_mov_b32_e32 v58, v242
	v_mov_b32_e32 v59, v243
	v_mov_b32_e32 v60, v244
	v_mov_b32_e32 v61, v245
	v_mov_b32_e32 v62, v246
	v_mov_b32_e32 v63, v247
	s_branch .LdtJ_epi
.LdtJ_next:
	s_add_i32 s27, s27, s22
	s_cmp_gt_i32 s27, 639
	s_cbranch_scc0 .LBB0_21

.LBB0_251:
	s_mul_hi_u32 s0, s27, 0xcccccccd
	s_lshr_b32 s0, s0, 4
	s_mul_i32 s1, s0, 20
	s_sub_i32 s30, s27, s1
	s_lshl_b32 s30, s30, 1
	v_writelane_b32 v255, s30, 57
	v_writelane_b32 v255, s0, 58
	v_mov_b32_e32 v2, v208
	s_ashr_i32 s31, s30, 31
	v_ashrrev_i32_e32 v3, 6, v2
	v_lshrrev_b32_e32 v0, 3, v2
	v_bfe_u32 v1, v2, 3, 3
	v_lshlrev_b32_e32 v5, 5, v3
	s_lshl_b64 s[36:37], s[30:31], 18
	v_readlane_b32 s38, v251, 27
	v_bitop3_b32 v4, v0, v2, 7 bitop3:0x28
	v_or_b32_e32 v0, v5, v1
	v_readlane_b32 s39, v251, 28
	s_add_u32 s36, s38, s36
	v_ashrrev_i32_e32 v1, 31, v0
	s_addc_u32 s37, s39, s37
	v_lshlrev_b64 v[0:1], 11, v[0:1]
	v_lshl_add_u64 v[0:1], s[36:37], 0, v[0:1]
	v_lshlrev_b32_e32 v128, 4, v4
	v_lshl_add_u64 v[64:65], v[0:1], 0, v[128:129]
	v_lshrrev_b32_e32 v0, 2, v2
	s_ashr_i32 s1, s0, 31
	v_and_b32_e32 v0, 8, v0
	v_bfe_u32 v1, v2, 3, 2
	s_lshl_b64 s[38:39], s[0:1], 18
	v_or3_b32 v0, v0, v1, v5
	s_add_u32 s38, s24, s38
	v_ashrrev_i32_e32 v1, 31, v0
	s_addc_u32 s39, s25, s39
	v_lshlrev_b64 v[0:1], 11, v[0:1]
	v_lshl_add_u64 v[0:1], s[38:39], 0, v[0:1]
	v_lshlrev_b32_e32 v80, 12, v3
	v_lshl_add_u64 v[66:67], v[0:1], 0, v[128:129]
	v_readfirstlane_b32 s1, v80
	v_or_b32_e32 v0, 0x400, v80
	s_waitcnt lgkmcnt(0)
	s_barrier
	s_mov_b32 m0, s1
	s_mov_b64 s[36:37], 0x4000
	v_readfirstlane_b32 s1, v0
	v_or_b32_e32 v0, 0x800, v80
	global_load_lds_dwordx4 v[64:65], off
	v_lshl_add_u64 v[68:69], v[64:65], 0, s[36:37]
	s_mov_b32 m0, s1
	s_mov_b64 s[36:37], 0x8000
	v_readfirstlane_b32 s1, v0
	v_or_b32_e32 v0, 0xc00, v80
	global_load_lds_dwordx4 v[68:69], off
	v_lshl_add_u64 v[70:71], v[64:65], 0, s[36:37]
	s_mov_b32 m0, s1
	s_mov_b64 s[38:39], 0xc000
	v_readfirstlane_b32 s1, v0
	v_add_u32_e32 v0, 0x4000, v80
	global_load_lds_dwordx4 v[70:71], off
	v_lshl_add_u64 v[72:73], v[64:65], 0, s[38:39]
	s_mov_b32 m0, s1
	v_readfirstlane_b32 s1, v0
	v_add_u32_e32 v0, 0x4400, v80
	global_load_lds_dwordx4 v[72:73], off
	s_mov_b32 m0, s1
	v_readfirstlane_b32 s1, v0
	v_add_u32_e32 v0, 0x4800, v80
	global_load_lds_dwordx4 v[66:67], off
	v_lshl_add_u64 v[74:75], v[66:67], 0, s[36:37]
	s_mov_b32 m0, s1
	s_mov_b64 s[36:37], 0x2000
	v_readfirstlane_b32 s1, v0
	v_add_u32_e32 v0, 0x4c00, v80
	global_load_lds_dwordx4 v[74:75], off
	v_lshl_add_u64 v[76:77], v[66:67], 0, s[36:37]
	s_mov_b32 m0, s1
	s_mov_b64 s[36:37], 0xa000
	v_readfirstlane_b32 s1, v0
	global_load_lds_dwordx4 v[76:77], off
	v_lshl_add_u64 v[78:79], v[66:67], 0, s[36:37]
	s_mov_b32 m0, s1
	v_and_b32_e32 v0, 7, v2
	global_load_lds_dwordx4 v[78:79], off
	v_lshlrev_b32_e32 v1, 7, v2
	v_lshlrev_b32_e32 v0, 4, v0
	v_and_b32_e32 v1, 0x780, v1
	v_bitop3_b32 v0, v0, v2, 48 bitop3:0x78
	v_or_b32_e32 v81, v0, v1
	v_bitop3_b32 v82, v0, 64, v1 bitop3:0x36
	v_lshlrev_b32_e32 v0, 6, v2
	v_and_b32_e32 v83, 0xffffe000, v0
	v_lshlrev_b32_e32 v0, 13, v3
	v_and_b32_e32 v0, 0x2000, v0
	v_or_b32_e32 v84, 0x4000, v0
	v_mov_b32_e32 v0, 0
	s_mov_b32 s1, 64
	s_mov_b32 s28, 0
	v_mov_b32_e32 v1, v0
	v_mov_b32_e32 v2, v0
	v_mov_b32_e32 v3, v0
	v_mov_b32_e32 v4, v0
	v_mov_b32_e32 v5, v0
	v_mov_b32_e32 v6, v0
	v_mov_b32_e32 v7, v0
	v_mov_b32_e32 v8, v0
	v_mov_b32_e32 v9, v0
	v_mov_b32_e32 v10, v0
	v_mov_b32_e32 v11, v0
	v_mov_b32_e32 v12, v0
	v_mov_b32_e32 v13, v0
	v_mov_b32_e32 v14, v0
	v_mov_b32_e32 v15, v0
	v_mov_b32_e32 v16, v0
	v_mov_b32_e32 v17, v0
	v_mov_b32_e32 v18, v0
	v_mov_b32_e32 v19, v0
	v_mov_b32_e32 v20, v0
	v_mov_b32_e32 v21, v0
	v_mov_b32_e32 v22, v0
	v_mov_b32_e32 v23, v0
	v_mov_b32_e32 v24, v0
	v_mov_b32_e32 v25, v0
	v_mov_b32_e32 v26, v0
	v_mov_b32_e32 v27, v0
	v_mov_b32_e32 v28, v0
	v_mov_b32_e32 v29, v0
	v_mov_b32_e32 v30, v0
	v_mov_b32_e32 v31, v0
	v_mov_b32_e32 v32, v0
	v_mov_b32_e32 v33, v0
	v_mov_b32_e32 v34, v0
	v_mov_b32_e32 v35, v0
	v_mov_b32_e32 v36, v0
	v_mov_b32_e32 v37, v0
	v_mov_b32_e32 v38, v0
	v_mov_b32_e32 v39, v0
	v_mov_b32_e32 v40, v0
	v_mov_b32_e32 v41, v0
	v_mov_b32_e32 v42, v0
	v_mov_b32_e32 v43, v0
	v_mov_b32_e32 v44, v0
	v_mov_b32_e32 v45, v0
	v_mov_b32_e32 v46, v0
	v_mov_b32_e32 v47, v0
	v_mov_b32_e32 v48, v0
	v_mov_b32_e32 v49, v0
	v_mov_b32_e32 v50, v0
	v_mov_b32_e32 v51, v0
	v_mov_b32_e32 v52, v0
	v_mov_b32_e32 v53, v0
	v_mov_b32_e32 v54, v0
	v_mov_b32_e32 v55, v0
	v_mov_b32_e32 v56, v0
	v_mov_b32_e32 v57, v0
	v_mov_b32_e32 v58, v0
	v_mov_b32_e32 v59, v0
	v_mov_b32_e32 v60, v0
	v_mov_b32_e32 v61, v0
	v_mov_b32_e32 v62, v0
	v_mov_b32_e32 v63, v0
	v_readlane_b32 s36, v251, 27
	v_readlane_b32 s37, v251, 28
	v_readlane_b32 s31, v255, 57
	s_lshl_b32 s31, s31, 18
	s_add_u32 s36, s36, s31
	s_addc_u32 s37, s37, 0
	v_readlane_b32 s31, v255, 58
	s_lshl_b32 s31, s31, 18
	s_add_u32 s38, s24, s31
	s_addc_u32 s39, s25, 0
	v_add_u32_e32 v126, v83, v81
	v_add_u32_e32 v133, v83, v82
	v_add_u32_e32 v127, v84, v81
	v_add_u32_e32 v128, v84, v82
	v_readfirstlane_b32 s26, v80
	v_subrev_u32_e32 v82, s36, v64
	v_subrev_u32_e32 v83, s38, v66
	s_add_u32 m0, s26, 0x8000
	s_add_u32 s60, s36, 0x40000
	s_addc_u32 s61, s37, 0
	global_load_lds_dwordx4 v82, s[60:61]
	s_add_u32 m0, s26, 0x8400
	s_add_u32 s60, s36, 0x44000
	s_addc_u32 s61, s37, 0
	global_load_lds_dwordx4 v82, s[60:61]
	s_add_u32 m0, s26, 0x8800
	s_add_u32 s60, s36, 0x48000
	s_addc_u32 s61, s37, 0
	global_load_lds_dwordx4 v82, s[60:61]
	s_add_u32 m0, s26, 0x8c00
	s_add_u32 s60, s36, 0x4c000
	s_addc_u32 s61, s37, 0
	global_load_lds_dwordx4 v82, s[60:61]
	v_mov_b32_e32 v160, 0
	v_mov_b32_e32 v161, 0
	v_mov_b32_e32 v162, 0
	v_mov_b32_e32 v163, 0
	v_mov_b32_e32 v164, 0
	v_mov_b32_e32 v165, 0
	v_mov_b32_e32 v166, 0
	v_mov_b32_e32 v167, 0
	v_mov_b32_e32 v168, 0
	v_mov_b32_e32 v169, 0
	v_mov_b32_e32 v170, 0
	v_mov_b32_e32 v171, 0
	v_mov_b32_e32 v172, 0
	v_mov_b32_e32 v173, 0
	v_mov_b32_e32 v174, 0
	v_mov_b32_e32 v175, 0
	v_mov_b32_e32 v176, 0
	v_mov_b32_e32 v177, 0
	v_mov_b32_e32 v178, 0
	v_mov_b32_e32 v179, 0
	v_mov_b32_e32 v180, 0
	v_mov_b32_e32 v181, 0
	v_mov_b32_e32 v182, 0
	v_mov_b32_e32 v183, 0
	v_mov_b32_e32 v184, 0
	v_mov_b32_e32 v185, 0
	v_mov_b32_e32 v186, 0
	v_mov_b32_e32 v187, 0
	v_mov_b32_e32 v188, 0
	v_mov_b32_e32 v189, 0
	v_mov_b32_e32 v190, 0
	v_mov_b32_e32 v191, 0
	v_mov_b32_e32 v192, 0
	v_mov_b32_e32 v193, 0
	v_mov_b32_e32 v194, 0
	v_mov_b32_e32 v195, 0
	v_mov_b32_e32 v196, 0
	v_mov_b32_e32 v197, 0
	v_mov_b32_e32 v198, 0
	v_mov_b32_e32 v199, 0
	v_mov_b32_e32 v200, 0
	v_mov_b32_e32 v201, 0
	v_mov_b32_e32 v202, 0
	v_mov_b32_e32 v203, 0
	v_mov_b32_e32 v204, 0
	v_mov_b32_e32 v205, 0
	v_mov_b32_e32 v206, 0
	v_mov_b32_e32 v207, 0
	v_mov_b32_e32 v232, 0
	v_mov_b32_e32 v233, 0
	v_mov_b32_e32 v234, 0
	v_mov_b32_e32 v235, 0
	v_mov_b32_e32 v236, 0
	v_mov_b32_e32 v237, 0
	v_mov_b32_e32 v238, 0
	v_mov_b32_e32 v239, 0
	v_mov_b32_e32 v240, 0
	v_mov_b32_e32 v241, 0
	v_mov_b32_e32 v242, 0
	v_mov_b32_e32 v243, 0
	v_mov_b32_e32 v244, 0
	v_mov_b32_e32 v245, 0
	v_mov_b32_e32 v246, 0
	v_mov_b32_e32 v247, 0
	s_mov_b32 s1, 0
	s_mov_b32 s28, 0
.LBB0_252:
	s_waitcnt vmcnt(0)
	s_waitcnt lgkmcnt(0)
	s_barrier
	s_add_i32 s31, s1, 64
	s_cmp_ge_i32 s31, 1024
	s_cbranch_scc1 .LdtB_nb
	s_xor_b32 s31, s28, 0x8000
	s_add_u32 s31, s31, s26
	s_add_u32 m0, s31, 0x4000
	s_add_u32 s60, s38, 0x80
	s_addc_u32 s61, s39, 0
	global_load_lds_dwordx4 v83, s[60:61]
	s_add_u32 m0, s31, 0x4400
	s_add_u32 s60, s38, 0x8080
	s_addc_u32 s61, s39, 0
	global_load_lds_dwordx4 v83, s[60:61]
	s_add_u32 m0, s31, 0x4800
	s_add_u32 s60, s38, 0x2080
	s_addc_u32 s61, s39, 0
	global_load_lds_dwordx4 v83, s[60:61]
	s_add_u32 m0, s31, 0x4c00
	s_add_u32 s60, s38, 0xa080
	s_addc_u32 s61, s39, 0
	global_load_lds_dwordx4 v83, s[60:61]
.LdtB_nb:
	v_add_u32_e32 v80, s28, v127
	v_add_u32_e32 v81, s28, v128
	ds_read_b128 v[86:89], v126
	ds_read_b128 v[90:93], v126 offset:2048
	ds_read_b128 v[94:97], v126 offset:4096
	ds_read_b128 v[98:101], v126 offset:6144
	ds_read_b128 v[102:105], v80
	ds_read_b128 v[106:109], v80 offset:2048
	ds_read_b128 v[110:113], v80 offset:4096
	ds_read_b128 v[114:117], v80 offset:6144
	ds_read_b128 v[118:121], v133
	ds_read_b128 v[122:125], v133 offset:2048
	ds_read_b128 v[134:137], v133 offset:4096
	ds_read_b128 v[138:141], v133 offset:6144
	ds_read_b128 v[64:67], v126 offset:32768
	ds_read_b128 v[68:71], v126 offset:34816
	ds_read_b128 v[72:75], v126 offset:36864
	ds_read_b128 v[76:79], v126 offset:38912
	ds_read_b128 v[142:145], v81
	ds_read_b128 v[146:149], v81 offset:2048
	ds_read_b128 v[150:153], v81 offset:4096
	ds_read_b128 v[154:157], v81 offset:6144
	s_waitcnt lgkmcnt(12)
	v_mfma_f32_16x16x32_bf16 v[60:63], v[102:105], v[86:89], v[60:63]
	v_mfma_f32_16x16x32_bf16 v[56:59], v[106:109], v[86:89], v[56:59]
	v_mfma_f32_16x16x32_bf16 v[52:55], v[110:113], v[86:89], v[52:55]
	v_mfma_f32_16x16x32_bf16 v[48:51], v[114:117], v[86:89], v[48:51]
	v_mfma_f32_16x16x32_bf16 v[44:47], v[102:105], v[90:93], v[44:47]
	v_mfma_f32_16x16x32_bf16 v[40:43], v[106:109], v[90:93], v[40:43]
	v_mfma_f32_16x16x32_bf16 v[36:39], v[110:113], v[90:93], v[36:39]
	v_mfma_f32_16x16x32_bf16 v[32:35], v[114:117], v[90:93], v[32:35]
	v_mfma_f32_16x16x32_bf16 v[28:31], v[102:105], v[94:97], v[28:31]
	v_mfma_f32_16x16x32_bf16 v[24:27], v[106:109], v[94:97], v[24:27]
	v_mfma_f32_16x16x32_bf16 v[20:23], v[110:113], v[94:97], v[20:23]
	v_mfma_f32_16x16x32_bf16 v[12:15], v[102:105], v[98:101], v[12:15]
	v_mfma_f32_16x16x32_bf16 v[8:11], v[106:109], v[98:101], v[8:11]
	v_mfma_f32_16x16x32_bf16 v[4:7], v[110:113], v[98:101], v[4:7]
	v_mfma_f32_16x16x32_bf16 v[0:3], v[114:117], v[98:101], v[0:3]
	v_mfma_f32_16x16x32_bf16 v[16:19], v[114:117], v[94:97], v[16:19]
	ds_read_b128 v[86:89], v133 offset:32768
	ds_read_b128 v[90:93], v133 offset:34816
	ds_read_b128 v[94:97], v133 offset:36864
	ds_read_b128 v[98:101], v133 offset:38912
	s_waitcnt lgkmcnt(8)
	v_mfma_f32_16x16x32_bf16 v[244:247], v[102:105], v[64:67], v[244:247]
	v_mfma_f32_16x16x32_bf16 v[240:243], v[106:109], v[64:67], v[240:243]
	v_mfma_f32_16x16x32_bf16 v[236:239], v[110:113], v[64:67], v[236:239]
	v_mfma_f32_16x16x32_bf16 v[232:235], v[114:117], v[64:67], v[232:235]
	v_mfma_f32_16x16x32_bf16 v[204:207], v[102:105], v[68:71], v[204:207]
	v_mfma_f32_16x16x32_bf16 v[200:203], v[106:109], v[68:71], v[200:203]
	v_mfma_f32_16x16x32_bf16 v[196:199], v[110:113], v[68:71], v[196:199]
	v_mfma_f32_16x16x32_bf16 v[192:195], v[114:117], v[68:71], v[192:195]
	v_mfma_f32_16x16x32_bf16 v[188:191], v[102:105], v[72:75], v[188:191]
	v_mfma_f32_16x16x32_bf16 v[184:187], v[106:109], v[72:75], v[184:187]
	v_mfma_f32_16x16x32_bf16 v[180:183], v[110:113], v[72:75], v[180:183]
	v_mfma_f32_16x16x32_bf16 v[172:175], v[102:105], v[76:79], v[172:175]
	v_mfma_f32_16x16x32_bf16 v[168:171], v[106:109], v[76:79], v[168:171]
	v_mfma_f32_16x16x32_bf16 v[164:167], v[110:113], v[76:79], v[164:167]
	v_mfma_f32_16x16x32_bf16 v[160:163], v[114:117], v[76:79], v[160:163]
	v_mfma_f32_16x16x32_bf16 v[176:179], v[114:117], v[72:75], v[176:179]
	s_waitcnt lgkmcnt(0)
	s_barrier
	s_add_i32 s31, s1, 64
	s_cmp_ge_i32 s31, 1024
	s_cbranch_scc1 .LdtB_na
	s_add_u32 m0, s26, 0x0
	s_add_u32 s60, s36, 0x80
	s_addc_u32 s61, s37, 0
	global_load_lds_dwordx4 v82, s[60:61]
	s_add_u32 m0, s26, 0x400
	s_add_u32 s60, s36, 0x4080
	s_addc_u32 s61, s37, 0
	global_load_lds_dwordx4 v82, s[60:61]
	s_add_u32 m0, s26, 0x800
	s_add_u32 s60, s36, 0x8080
	s_addc_u32 s61, s37, 0
	global_load_lds_dwordx4 v82, s[60:61]
	s_add_u32 m0, s26, 0xc00
	s_add_u32 s60, s36, 0xc080
	s_addc_u32 s61, s37, 0
	global_load_lds_dwordx4 v82, s[60:61]
	s_add_u32 m0, s26, 0x8000
	s_add_u32 s60, s36, 0x40080
	s_addc_u32 s61, s37, 0
	global_load_lds_dwordx4 v82, s[60:61]
	s_add_u32 m0, s26, 0x8400
	s_add_u32 s60, s36, 0x44080
	s_addc_u32 s61, s37, 0
	global_load_lds_dwordx4 v82, s[60:61]
	s_add_u32 m0, s26, 0x8800
	s_add_u32 s60, s36, 0x48080
	s_addc_u32 s61, s37, 0
	global_load_lds_dwordx4 v82, s[60:61]
	s_add_u32 m0, s26, 0x8c00
	s_add_u32 s60, s36, 0x4c080
	s_addc_u32 s61, s37, 0
	global_load_lds_dwordx4 v82, s[60:61]
.LdtB_na:
	s_nop 0
	v_mfma_f32_16x16x32_bf16 v[60:63], v[142:145], v[118:121], v[60:63]
	v_mfma_f32_16x16x32_bf16 v[56:59], v[146:149], v[118:121], v[56:59]
	v_mfma_f32_16x16x32_bf16 v[52:55], v[150:153], v[118:121], v[52:55]
	v_mfma_f32_16x16x32_bf16 v[48:51], v[154:157], v[118:121], v[48:51]
	v_mfma_f32_16x16x32_bf16 v[44:47], v[142:145], v[122:125], v[44:47]
	v_mfma_f32_16x16x32_bf16 v[40:43], v[146:149], v[122:125], v[40:43]
	v_mfma_f32_16x16x32_bf16 v[36:39], v[150:153], v[122:125], v[36:39]
	v_mfma_f32_16x16x32_bf16 v[32:35], v[154:157], v[122:125], v[32:35]
	v_mfma_f32_16x16x32_bf16 v[28:31], v[142:145], v[134:137], v[28:31]
	v_mfma_f32_16x16x32_bf16 v[24:27], v[146:149], v[134:137], v[24:27]
	v_mfma_f32_16x16x32_bf16 v[20:23], v[150:153], v[134:137], v[20:23]
	v_mfma_f32_16x16x32_bf16 v[16:19], v[154:157], v[134:137], v[16:19]
	v_mfma_f32_16x16x32_bf16 v[12:15], v[142:145], v[138:141], v[12:15]
	v_mfma_f32_16x16x32_bf16 v[8:11], v[146:149], v[138:141], v[8:11]
	v_mfma_f32_16x16x32_bf16 v[4:7], v[150:153], v[138:141], v[4:7]
	v_mfma_f32_16x16x32_bf16 v[0:3], v[154:157], v[138:141], v[0:3]
	v_mfma_f32_16x16x32_bf16 v[244:247], v[142:145], v[86:89], v[244:247]
	v_mfma_f32_16x16x32_bf16 v[240:243], v[146:149], v[86:89], v[240:243]
	v_mfma_f32_16x16x32_bf16 v[236:239], v[150:153], v[86:89], v[236:239]
	v_mfma_f32_16x16x32_bf16 v[232:235], v[154:157], v[86:89], v[232:235]
	v_mfma_f32_16x16x32_bf16 v[204:207], v[142:145], v[90:93], v[204:207]
	v_mfma_f32_16x16x32_bf16 v[200:203], v[146:149], v[90:93], v[200:203]
	v_mfma_f32_16x16x32_bf16 v[196:199], v[150:153], v[90:93], v[196:199]
	v_mfma_f32_16x16x32_bf16 v[192:195], v[154:157], v[90:93], v[192:195]
	v_mfma_f32_16x16x32_bf16 v[188:191], v[142:145], v[94:97], v[188:191]
	v_mfma_f32_16x16x32_bf16 v[184:187], v[146:149], v[94:97], v[184:187]
	v_mfma_f32_16x16x32_bf16 v[180:183], v[150:153], v[94:97], v[180:183]
	v_mfma_f32_16x16x32_bf16 v[176:179], v[154:157], v[94:97], v[176:179]
	v_mfma_f32_16x16x32_bf16 v[172:175], v[142:145], v[98:101], v[172:175]
	v_mfma_f32_16x16x32_bf16 v[168:171], v[146:149], v[98:101], v[168:171]
	v_mfma_f32_16x16x32_bf16 v[164:167], v[150:153], v[98:101], v[164:167]
	v_mfma_f32_16x16x32_bf16 v[160:163], v[154:157], v[98:101], v[160:163]
	s_add_u32 s36, s36, 0x80
	s_addc_u32 s37, s37, 0
	s_add_u32 s38, s38, 0x80
	s_addc_u32 s39, s39, 0
	s_xor_b32 s28, s28, 0x8000
	s_add_i32 s1, s1, 64
	s_cmp_lt_i32 s1, 1024
	s_cbranch_scc1 .LBB0_252
	s_waitcnt vmcnt(0)
	v_mov_b32_e32 v64, v208
	s_waitcnt lgkmcnt(0)
	s_barrier
	s_mov_b32 s31, 0
	v_writelane_b32 v255, s31, 59
	v_readlane_b32 s30, v255, 57
	v_readlane_b32 s0, v255, 58
.LdtB_epi:
	v_mov_b32_e32 v65, v208
	v_and_b32_e32 v67, 15, v64
	v_lshrrev_b32_e32 v64, 1, v64
	v_and_b32_e32 v64, 24, v64
	v_ashrrev_i32_e32 v66, 1, v65
	s_movk_i32 s1, 0xffc0
	v_and_or_b32 v64, v65, 64, v64
	v_and_or_b32 v65, v66, s1, v67
	v_lshl_add_u32 v65, s30, 7, v65
	s_lshl_b32 s0, s0, 7
	v_cvt_pk_bf16_f32 v60, v60, v61
	v_cvt_pk_bf16_f32 v61, v62, v63
	v_cvt_pk_bf16_f32 v62, v56, v57
	v_mov_b64_e32 v[56:57], s[70:71]
	s_ashr_i32 s1, s0, 31
	v_cvt_pk_bf16_f32 v44, v44, v45
	v_cvt_pk_bf16_f32 v45, v46, v47
	v_cvt_pk_bf16_f32 v46, v40, v41
	v_or_b32_e32 v40, 16, v65
	v_cvt_pk_bf16_f32 v28, v28, v29
	v_cvt_pk_bf16_f32 v29, v30, v31
	v_cvt_pk_bf16_f32 v30, v24, v25
	v_or_b32_e32 v24, 32, v65
	v_cvt_pk_bf16_f32 v12, v12, v13
	v_cvt_pk_bf16_f32 v13, v14, v15
	v_cvt_pk_bf16_f32 v14, v8, v9
	v_or_b32_e32 v8, 48, v65
	v_cvt_pk_bf16_f32 v63, v58, v59
	v_mad_i64_i32 v[58:59], s[30:31], v65, s40, v[56:57]
	s_lshl_b64 s[0:1], s[0:1], 1
	v_mad_i64_i32 v[40:41], s[30:31], v40, s40, v[56:57]
	v_mad_i64_i32 v[24:25], s[30:31], v24, s40, v[56:57]
	v_mad_i64_i32 v[8:9], s[30:31], v8, s40, v[56:57]
	v_lshl_add_u64 v[58:59], v[58:59], 0, s[0:1]
	v_lshlrev_b32_e32 v128, 1, v64
	v_lshl_add_u64 v[40:41], v[40:41], 0, s[0:1]
	v_lshl_add_u64 v[24:25], v[24:25], 0, s[0:1]
	v_lshl_add_u64 v[8:9], v[8:9], 0, s[0:1]
	v_lshl_add_u64 v[58:59], v[58:59], 0, v[128:129]
	v_cvt_pk_bf16_f32 v52, v52, v53
	v_cvt_pk_bf16_f32 v53, v54, v55
	v_cvt_pk_bf16_f32 v54, v48, v49
	v_cvt_pk_bf16_f32 v55, v50, v51
	v_cvt_pk_bf16_f32 v47, v42, v43
	v_lshl_add_u64 v[40:41], v[40:41], 0, v[128:129]
	v_cvt_pk_bf16_f32 v36, v36, v37
	v_cvt_pk_bf16_f32 v37, v38, v39
	v_cvt_pk_bf16_f32 v38, v32, v33
	v_cvt_pk_bf16_f32 v39, v34, v35
	v_cvt_pk_bf16_f32 v31, v26, v27
	v_lshl_add_u64 v[24:25], v[24:25], 0, v[128:129]
	v_cvt_pk_bf16_f32 v20, v20, v21
	v_cvt_pk_bf16_f32 v21, v22, v23
	v_cvt_pk_bf16_f32 v22, v16, v17
	v_cvt_pk_bf16_f32 v23, v18, v19
	v_cvt_pk_bf16_f32 v15, v10, v11
	v_lshl_add_u64 v[8:9], v[8:9], 0, v[128:129]
	v_cvt_pk_bf16_f32 v4, v4, v5
	v_cvt_pk_bf16_f32 v5, v6, v7
	v_cvt_pk_bf16_f32 v6, v0, v1
	v_cvt_pk_bf16_f32 v7, v2, v3
	global_store_dwordx4 v[58:59], v[60:63], off
	global_store_dwordx4 v[58:59], v[52:55], off offset:64
	global_store_dwordx4 v[40:41], v[44:47], off
	global_store_dwordx4 v[40:41], v[36:39], off offset:64
	global_store_dwordx4 v[24:25], v[28:31], off
	global_store_dwordx4 v[24:25], v[20:23], off offset:64
	global_store_dwordx4 v[8:9], v[12:15], off
	global_store_dwordx4 v[8:9], v[4:7], off offset:64
	v_readlane_b32 s31, v255, 59
	s_cmp_lg_u32 s31, 0
	s_cbranch_scc1 .LdtB_next
	s_mov_b32 s31, 1
	v_writelane_b32 v255, s31, 59
	v_readlane_b32 s30, v255, 57
	v_readlane_b32 s0, v255, 58
	s_add_i32 s30, s30, 1
	v_mov_b32_e32 v64, v208
	v_mov_b32_e32 v0, v160
	v_mov_b32_e32 v1, v161
	v_mov_b32_e32 v2, v162
	v_mov_b32_e32 v3, v163
	v_mov_b32_e32 v4, v164
	v_mov_b32_e32 v5, v165
	v_mov_b32_e32 v6, v166
	v_mov_b32_e32 v7, v167
	v_mov_b32_e32 v8, v168
	v_mov_b32_e32 v9, v169
	v_mov_b32_e32 v10, v170
	v_mov_b32_e32 v11, v171
	v_mov_b32_e32 v12, v172
	v_mov_b32_e32 v13, v173
	v_mov_b32_e32 v14, v174
	v_mov_b32_e32 v15, v175
	v_mov_b32_e32 v16, v176
	v_mov_b32_e32 v17, v177
	v_mov_b32_e32 v18, v178
	v_mov_b32_e32 v19, v179
	v_mov_b32_e32 v20, v180
	v_mov_b32_e32 v21, v181
	v_mov_b32_e32 v22, v182
	v_mov_b32_e32 v23, v183
	v_mov_b32_e32 v24, v184
	v_mov_b32_e32 v25, v185
	v_mov_b32_e32 v26, v186
	v_mov_b32_e32 v27, v187
	v_mov_b32_e32 v28, v188
	v_mov_b32_e32 v29, v189
	v_mov_b32_e32 v30, v190
	v_mov_b32_e32 v31, v191
	v_mov_b32_e32 v32, v192
	v_mov_b32_e32 v33, v193
	v_mov_b32_e32 v34, v194
	v_mov_b32_e32 v35, v195
	v_mov_b32_e32 v36, v196
	v_mov_b32_e32 v37, v197
	v_mov_b32_e32 v38, v198
	v_mov_b32_e32 v39, v199
	v_mov_b32_e32 v40, v200
	v_mov_b32_e32 v41, v201
	v_mov_b32_e32 v42, v202
	v_mov_b32_e32 v43, v203
	v_mov_b32_e32 v44, v204
	v_mov_b32_e32 v45, v205
	v_mov_b32_e32 v46, v206
	v_mov_b32_e32 v47, v207
	v_mov_b32_e32 v48, v232
	v_mov_b32_e32 v49, v233
	v_mov_b32_e32 v50, v234
	v_mov_b32_e32 v51, v235
	v_mov_b32_e32 v52, v236
	v_mov_b32_e32 v53, v237
	v_mov_b32_e32 v54, v238
	v_mov_b32_e32 v55, v239
	v_mov_b32_e32 v56, v240
	v_mov_b32_e32 v57, v241
	v_mov_b32_e32 v58, v242
	v_mov_b32_e32 v59, v243
	v_mov_b32_e32 v60, v244
	v_mov_b32_e32 v61, v245
	v_mov_b32_e32 v62, v246
	v_mov_b32_e32 v63, v247
	s_branch .LdtB_epi
.LdtB_next:
	s_add_i32 s27, s27, s22
	s_cmp_gt_i32 s27, 1019
	s_cbranch_scc0 .LBB0_251
